# NA step body: LDS fragment reads batched (eight K-fragment reads, one wait, eight MFMAs; V fragments seven tiles at a time) on top of the widened-store version
# speedup vs baseline: 1.0008x; 1.0008x over previous
; DI unsigned pk2(float lo, float hi) { return pg8::cvt_pk_bf16(lo, hi); }
; DI float fexp2(float x) { return __builtin_amdgcn_exp2f(x); }
; DI void na_phase(const Params& P, LAS unsigned char* lds, int r, const bf16* QKV, bf16* CAT) {
;     ...
;             if (kr >= rs && kr < rs + 8) {
;                 const int dr = kr - rin + 7;
; #pragma unroll
;                 for (int tl = 0; tl < 2; ++tl) {
;                     const int cb = cbp + tl, c0 = cb * 16, blk = min(max(16 * cb - 8, 0), 32);
;                     f32x4 sc[2];
; #pragma unroll
;                     for (int hf = 0; hf < 2; ++hf) { sc[hf] = (f32x4){0.f, 0.f, 0.f, 0.f};
; #pragma unroll
;                         for (int ks = 0; ks < 4; ++ks) sc[hf] = mfma16(frag_row(KI, PITCH, blk + 16 * hf, 32 * ks, lane), qa[tl][ks], sc[hf]); }
;                     float mx = -INFINITY; float bvs[2][4];
; #pragma unroll
;                     for (int hf = 0; hf < 2; ++hf)
; #pragma unroll
;                         for (int i = 0; i < 4; ++i) bvs[hf][i] = RB[dr * 31 + max(dco[tl][hf][i], 0)];
;                     asm volatile("" : "+v"(bvs[0][0]), "+v"(bvs[0][1]), "+v"(bvs[0][2]), "+v"(bvs[0][3]), "+v"(bvs[1][0]), "+v"(bvs[1][1]), "+v"(bvs[1][2]), "+v"(bvs[1][3]));
; #pragma unroll
;                     for (int hf = 0; hf < 2; ++hf)
; #pragma unroll
;                         for (int i = 0; i < 4; ++i) { const float sv = dco[tl][hf][i] >= 0 ? sc[hf][i] * QK_SCALE + bvs[hf][i] : -INFINITY; sc[hf][i] = sv; mx = fmaxf(mx, sv); }
;                     if (kr == rs) { mx = fmaxf(mx, __shfl_xor(mx, 16)); mx = fmaxf(mx, __shfl_xor(mx, 32)); mrun[tl] = mx; }
;                     float ps = 0.f;
; #pragma unroll
;                     for (int hf = 0; hf < 2; ++hf)
; #pragma unroll
;                         for (int i = 0; i < 4; ++i) { const float p = fexp2(fminf((sc[hf][i] - mrun[tl]) * LOG2E, 100.0f)); sc[hf][i] = p; ps += p; }
;                     lrun[tl] += ps;
;                     v4u pw; pw.x = pk2(sc[0][0], sc[0][1]); pw.y = pk2(sc[0][2], sc[0][3]); pw.z = pk2(sc[1][0], sc[1][1]); pw.w = pk2(sc[1][2], sc[1][3]);
;                     const bf16x8 pf = __builtin_bit_cast(bf16x8, pw);
; #pragma unroll
;                     for (int t = 0; t < 8; ++t) { oacc[tl][t] = mfma16(frag_tr2(VI, PITCH, blk, blk + 16, 16 * t, lane), pf, oacc[tl][t]); if ((t & 3) == 3) __builtin_amdgcn_sched_barrier(0); }
.LBB0_232:
	s_add_i32 s46, s62, s33
	s_add_i32 s67, s46, -2
	s_cmp_ge_i32 s67, s68
	s_cselect_b64 s[46:47], -1, 0
	s_cmp_lt_i32 s67, s70
	s_cselect_b64 s[80:81], -1, 0
	s_and_b64 s[46:47], s[46:47], s[80:81]
	s_andn2_b64 vcc, exec, s[46:47]
	s_cbranch_vccnz .LBB0_238
	s_add_i32 s47, s66, -2
	s_and_b32 s47, s47, 2
	s_mulk_i32 s47, 0x4400
	s_add_i32 s67, s47, 0
	v_add_u32_e32 v176, s67, v128
	v_add_u32_e32 v177, v176, v133
	ds_read_b128 v[178:181], v177
	ds_read_b128 v[216:219], v177 offset:64
	ds_read_b128 v[220:223], v177 offset:128
	ds_read_b128 v[224:227], v177 offset:192
	ds_read_b128 v[182:185], v177 offset:4352
	ds_read_b128 v[228:231], v177 offset:4416
	ds_read_b128 v[232:235], v177 offset:4480
	ds_read_b128 v[236:239], v177 offset:4544
	v_add_u32_e32 v190, s71, v149
	v_add_u32_e32 v191, s71, v148
	v_add_u32_e32 v192, s71, v147
	s_add_i32 s46, s83, s33
	s_cmp_eq_u32 s46, 2
	s_cselect_b64 s[80:81], -1, 0
	s_cmp_lg_u32 s46, 2
	v_add_u32_e32 v177, s71, v173
	s_waitcnt lgkmcnt(0)
	v_mfma_f32_16x16x32_bf16 v[178:181], v[178:181], v[0:3], 0
	v_mfma_f32_16x16x32_bf16 v[178:181], v[216:219], v[4:7], v[178:181]
	v_mfma_f32_16x16x32_bf16 v[178:181], v[220:223], v[8:11], v[178:181]
	v_mfma_f32_16x16x32_bf16 v[178:181], v[224:227], v[12:15], v[178:181]
	v_mfma_f32_16x16x32_bf16 v[182:185], v[182:185], v[0:3], 0
	v_mfma_f32_16x16x32_bf16 v[182:185], v[228:231], v[4:7], v[182:185]
	v_mfma_f32_16x16x32_bf16 v[182:185], v[232:235], v[8:11], v[182:185]
	v_mfma_f32_16x16x32_bf16 v[182:185], v[236:239], v[12:15], v[182:185]
	v_add_u32_e32 v186, s71, v172
	v_add_u32_e32 v187, s71, v171
	v_add_u32_e32 v188, s71, v151
	v_add_u32_e32 v189, s71, v150
	ds_read_b32 v192, v192
	ds_read_b32 v191, v191
	ds_read_b32 v190, v190
	ds_read_b32 v189, v189
	ds_read_b32 v188, v188
	ds_read_b32 v187, v187
	ds_read_b32 v186, v186
	ds_read_b32 v177, v177
	s_waitcnt lgkmcnt(0)
	s_nop 0
	v_fmac_f32_e32 v177, 0x3db504f3, v178
	v_fmac_f32_e32 v186, 0x3db504f3, v179
	v_fmac_f32_e32 v187, 0x3db504f3, v180
	v_fmac_f32_e32 v188, 0x3db504f3, v181
	v_fmac_f32_e32 v189, 0x3db504f3, v182
	v_fmac_f32_e32 v190, 0x3db504f3, v183
	v_fmac_f32_e32 v191, 0x3db504f3, v184
	v_fmac_f32_e32 v192, 0x3db504f3, v185
	v_cndmask_b32_e64 v177, v169, v177, s[6:7]
	v_cndmask_b32_e64 v178, v169, v186, s[8:9]
	v_cndmask_b32_e64 v179, v169, v187, s[10:11]
	v_cndmask_b32_e64 v180, v169, v188, s[12:13]
	v_cndmask_b32_e64 v181, v169, v189, s[14:15]
	v_cndmask_b32_e64 v182, v169, v190, s[16:17]
	v_cndmask_b32_e64 v183, v169, v191, s[18:19]
	v_cndmask_b32_e64 v184, v169, v192, s[20:21]
	s_cbranch_scc1 .LBB0_235
	v_max3_f32 v175, v177, s86, v178
	v_max3_f32 v175, v175, v179, v180
	v_cmp_lt_i32_e32 vcc, v163, v158
	v_max3_f32 v175, v175, v181, v182
	v_max3_f32 v175, v175, v183, v184
	v_cndmask_b32_e32 v185, v156, v163, vcc
	v_lshlrev_b32_e32 v185, 2, v185
	ds_bpermute_b32 v185, v185, v175
	v_cmp_lt_i32_e32 vcc, v164, v158
	s_waitcnt lgkmcnt(0)
	v_max_f32_e32 v185, v185, v185
	v_max_f32_e32 v175, v175, v185
	v_cndmask_b32_e32 v185, v156, v164, vcc
	v_lshlrev_b32_e32 v185, 2, v185
	ds_bpermute_b32 v185, v185, v175
	s_waitcnt lgkmcnt(0)
	v_max_f32_e32 v185, v185, v185
	v_max_f32_e32 v175, v175, v185
.LBB0_235:
	v_sub_f32_e32 v177, v177, v175
	v_sub_f32_e32 v178, v178, v175
	v_sub_f32_e32 v179, v179, v175
	v_sub_f32_e32 v180, v180, v175
	v_sub_f32_e32 v181, v181, v175
	v_sub_f32_e32 v182, v182, v175
	v_sub_f32_e32 v183, v183, v175
	v_sub_f32_e32 v184, v184, v175
	v_mul_f32_e32 v177, 0x3fb8aa3b, v177
	v_mul_f32_e32 v178, 0x3fb8aa3b, v178
	v_mul_f32_e32 v179, 0x3fb8aa3b, v179
	v_mul_f32_e32 v180, 0x3fb8aa3b, v180
	v_mul_f32_e32 v181, 0x3fb8aa3b, v181
	v_mul_f32_e32 v182, 0x3fb8aa3b, v182
	v_mul_f32_e32 v183, 0x3fb8aa3b, v183
	v_mul_f32_e32 v184, 0x3fb8aa3b, v184
	v_min_f32_e32 v177, 0x42c80000, v177
	v_min_f32_e32 v178, 0x42c80000, v178
	v_min_f32_e32 v179, 0x42c80000, v179
	v_min_f32_e32 v180, 0x42c80000, v180
	v_min_f32_e32 v181, 0x42c80000, v181
	v_min_f32_e32 v182, 0x42c80000, v182
	v_min_f32_e32 v183, 0x42c80000, v183
	v_min_f32_e32 v184, 0x42c80000, v184
	v_add3_u32 v196, s67, v135, v131
	v_exp_f32_e32 v177, v177
	v_exp_f32_e32 v178, v178
	v_exp_f32_e32 v179, v179
	v_exp_f32_e32 v180, v180
	v_exp_f32_e32 v181, v181
	v_exp_f32_e32 v182, v182
	v_exp_f32_e32 v183, v183
	v_exp_f32_e32 v184, v184
	v_cvt_pk_bf16_f32 v186, v177, v178
	v_cvt_pk_bf16_f32 v187, v179, v180
	v_cvt_pk_bf16_f32 v188, v181, v182
	v_cvt_pk_bf16_f32 v189, v183, v184
	v_add3_u32 v185, s67, v134, v131
	ds_read_b64_tr_b16 v[216:217], v185 offset:17408
	ds_read_b64_tr_b16 v[218:219], v196 offset:17408
	ds_read_b64_tr_b16 v[220:221], v185 offset:17440
	ds_read_b64_tr_b16 v[222:223], v196 offset:17440
	ds_read_b64_tr_b16 v[224:225], v185 offset:17472
	ds_read_b64_tr_b16 v[226:227], v196 offset:17472
	ds_read_b64_tr_b16 v[228:229], v185 offset:17504
	ds_read_b64_tr_b16 v[230:231], v196 offset:17504
	ds_read_b64_tr_b16 v[232:233], v185 offset:17536
	ds_read_b64_tr_b16 v[234:235], v196 offset:17536
	ds_read_b64_tr_b16 v[236:237], v185 offset:17568
	ds_read_b64_tr_b16 v[238:239], v196 offset:17568
	ds_read_b64_tr_b16 v[190:191], v185 offset:17600
	ds_read_b64_tr_b16 v[192:193], v196 offset:17600
	s_waitcnt lgkmcnt(0)
	v_mfma_f32_16x16x32_bf16 v[108:111], v[216:219], v[186:189], v[108:111]
	ds_read_b64_tr_b16 v[216:217], v185 offset:17632
	ds_read_b64_tr_b16 v[218:219], v196 offset:17632
	v_mfma_f32_16x16x32_bf16 v[104:107], v[220:223], v[186:189], v[104:107]
	v_mfma_f32_16x16x32_bf16 v[100:103], v[224:227], v[186:189], v[100:103]
	v_mfma_f32_16x16x32_bf16 v[96:99], v[228:231], v[186:189], v[96:99]
	v_mfma_f32_16x16x32_bf16 v[92:95], v[232:235], v[186:189], v[92:95]
	v_mfma_f32_16x16x32_bf16 v[88:91], v[236:239], v[186:189], v[88:91]
	v_mfma_f32_16x16x32_bf16 v[84:87], v[190:193], v[186:189], v[84:87]
	s_waitcnt lgkmcnt(0)
; DI unsigned pk2(float lo, float hi) { return pg8::cvt_pk_bf16(lo, hi); }
; DI float fexp2(float x) { return __builtin_amdgcn_exp2f(x); }
; DI f32x4 mfma16(bf16x8 a, bf16x8 b, f32x4 c) { return __builtin_amdgcn_mfma_f32_16x16x32_bf16(a, b, c, 0, 0, 0); }
; DI void na_phase(const Params& P, LAS unsigned char* lds, int r, const bf16* QKV, bf16* CAT) {
;     ...
;                 for (int tl = 0; tl < 2; ++tl) {
;                     const int cb = cbp + tl, c0 = cb * 16, blk = min(max(16 * cb - 8, 0), 32);
;                     f32x4 sc[2];
; #pragma unroll
;                     for (int hf = 0; hf < 2; ++hf) { sc[hf] = (f32x4){0.f, 0.f, 0.f, 0.f};
; #pragma unroll
;                         for (int ks = 0; ks < 4; ++ks) sc[hf] = mfma16(frag_row(KI, PITCH, blk + 16 * hf, 32 * ks, lane), qa[tl][ks], sc[hf]); }
;                     float mx = -INFINITY; float bvs[2][4];
; #pragma unroll
;                     for (int hf = 0; hf < 2; ++hf)
; #pragma unroll
;                         for (int i = 0; i < 4; ++i) bvs[hf][i] = RB[dr * 31 + max(dco[tl][hf][i], 0)];
;                     asm volatile("" : "+v"(bvs[0][0]), "+v"(bvs[0][1]), "+v"(bvs[0][2]), "+v"(bvs[0][3]), "+v"(bvs[1][0]), "+v"(bvs[1][1]), "+v"(bvs[1][2]), "+v"(bvs[1][3]));
; #pragma unroll
;                     for (int hf = 0; hf < 2; ++hf)
; #pragma unroll
;                         for (int i = 0; i < 4; ++i) { const float sv = dco[tl][hf][i] >= 0 ? sc[hf][i] * QK_SCALE + bvs[hf][i] : -INFINITY; sc[hf][i] = sv; mx = fmaxf(mx, sv); }
;                     if (kr == rs) { mx = fmaxf(mx, __shfl_xor(mx, 16)); mx = fmaxf(mx, __shfl_xor(mx, 32)); mrun[tl] = mx; }
;                     float ps = 0.f;
; #pragma unroll
;                     for (int hf = 0; hf < 2; ++hf)
; #pragma unroll
;                         for (int i = 0; i < 4; ++i) { const float p = fexp2(fminf((sc[hf][i] - mrun[tl]) * LOG2E, 100.0f)); sc[hf][i] = p; ps += p; }
;                     lrun[tl] += ps;
;                     v4u pw; pw.x = pk2(sc[0][0], sc[0][1]); pw.y = pk2(sc[0][2], sc[0][3]); pw.z = pk2(sc[1][0], sc[1][1]); pw.w = pk2(sc[1][2], sc[1][3]);
;                     const bf16x8 pf = __builtin_bit_cast(bf16x8, pw);
; #pragma unroll
;                     for (int t = 0; t < 8; ++t) { oacc[tl][t] = mfma16(frag_tr2(VI, PITCH, blk, blk + 16, 16 * t, lane), pf, oacc[tl][t]); if ((t & 3) == 3) __builtin_amdgcn_sched_barrier(0); }
	v_mfma_f32_16x16x32_bf16 v[80:83], v[216:219], v[186:189], v[80:83]
	v_add_u32_e32 v176, v176, v136
	ds_read_b128 v[192:195], v176
	ds_read_b128 v[216:219], v176 offset:64
	ds_read_b128 v[220:223], v176 offset:128
	ds_read_b128 v[224:227], v176 offset:192
	ds_read_b128 v[196:199], v176 offset:4352
	ds_read_b128 v[228:231], v176 offset:4416
	ds_read_b128 v[232:235], v176 offset:4480
	ds_read_b128 v[236:239], v176 offset:4544
	v_add_u32_e32 v185, s71, v145
	s_andn2_b64 vcc, exec, s[80:81]
	v_add_u32_e32 v191, s71, v117
	v_add_u32_e32 v190, s71, v119
	v_add_u32_e32 v176, s71, v146
	s_waitcnt lgkmcnt(0)
	v_mfma_f32_16x16x32_bf16 v[192:195], v[192:195], v[16:19], 0
	v_mfma_f32_16x16x32_bf16 v[192:195], v[216:219], v[20:23], v[192:195]
	v_mfma_f32_16x16x32_bf16 v[192:195], v[220:223], v[32:35], v[192:195]
	v_mfma_f32_16x16x32_bf16 v[192:195], v[224:227], v[36:39], v[192:195]
	v_mfma_f32_16x16x32_bf16 v[196:199], v[196:199], v[16:19], 0
	v_mfma_f32_16x16x32_bf16 v[196:199], v[228:231], v[20:23], v[196:199]
	v_mfma_f32_16x16x32_bf16 v[196:199], v[232:235], v[32:35], v[196:199]
	v_mfma_f32_16x16x32_bf16 v[196:199], v[236:239], v[36:39], v[196:199]
	s_nop 3
	v_add_u32_e32 v186, s71, v144
	v_add_u32_e32 v187, s71, v143
	v_add_u32_e32 v188, s71, v142
	v_add_u32_e32 v189, s71, v141
	ds_read_b32 v200, v191
	ds_read_b32 v201, v190
	ds_read_b32 v202, v189
	ds_read_b32 v203, v188
	ds_read_b32 v187, v187
	ds_read_b32 v186, v186
	ds_read_b32 v185, v185
	ds_read_b32 v176, v176
	s_waitcnt lgkmcnt(0)
	s_nop 0
	v_fmac_f32_e32 v176, 0x3db504f3, v192
	v_fmac_f32_e32 v185, 0x3db504f3, v193
	v_fmac_f32_e32 v186, 0x3db504f3, v194
	v_fmac_f32_e32 v187, 0x3db504f3, v195
	v_fmac_f32_e32 v203, 0x3db504f3, v196
	v_fmac_f32_e32 v202, 0x3db504f3, v197
	v_fmac_f32_e32 v201, 0x3db504f3, v198
	v_fmac_f32_e32 v200, 0x3db504f3, v199
	v_cndmask_b32_e64 v191, v169, v176, s[22:23]
	v_cndmask_b32_e64 v190, v169, v185, s[24:25]
	v_cndmask_b32_e64 v189, v169, v186, s[26:27]
	v_cndmask_b32_e64 v188, v169, v187, s[28:29]
	v_cndmask_b32_e64 v187, v169, v203, s[30:31]
	v_cndmask_b32_e64 v186, v169, v202, s[34:35]
	v_cndmask_b32_e64 v185, v169, v201, s[36:37]
	v_cndmask_b32_e64 v176, v169, v200, s[38:39]
	s_cbranch_vccnz .LBB0_237
	v_max3_f32 v174, v191, s86, v190
	v_max3_f32 v174, v174, v189, v188
	v_cmp_lt_i32_e32 vcc, v163, v158
	v_max3_f32 v174, v174, v187, v186
	v_max3_f32 v174, v174, v185, v176
	v_cndmask_b32_e32 v192, v156, v163, vcc
	v_lshlrev_b32_e32 v192, 2, v192
	ds_bpermute_b32 v192, v192, v174
	v_cmp_lt_i32_e32 vcc, v164, v158
	s_waitcnt lgkmcnt(0)
	v_max_f32_e32 v192, v192, v192
	v_max_f32_e32 v174, v174, v192
	v_cndmask_b32_e32 v192, v156, v164, vcc
	v_lshlrev_b32_e32 v192, 2, v192
	ds_bpermute_b32 v192, v192, v174
	s_waitcnt lgkmcnt(0)
	v_max_f32_e32 v192, v192, v192
	v_max_f32_e32 v174, v174, v192
.LBB0_237:
	v_add_f32_e32 v177, 0, v177
	v_add_f32_e32 v177, v178, v177
	v_add_f32_e32 v177, v179, v177
	v_add_f32_e32 v177, v180, v177
	v_add_f32_e32 v177, v181, v177
	v_add_f32_e32 v177, v182, v177
	v_add_f32_e32 v177, v183, v177
	v_add_f32_e32 v177, v184, v177
	v_add_f32_e32 v121, v121, v177
	v_sub_f32_e32 v177, v191, v174
	v_mul_f32_e32 v177, 0x3fb8aa3b, v177
	v_sub_f32_e32 v179, v190, v174
	v_min_f32_e32 v177, 0x42c80000, v177
	v_mul_f32_e32 v179, 0x3fb8aa3b, v179
	v_sub_f32_e32 v180, v189, v174
	v_exp_f32_e32 v177, v177
	v_min_f32_e32 v179, 0x42c80000, v179
	v_mul_f32_e32 v180, 0x3fb8aa3b, v180
	v_sub_f32_e32 v181, v188, v174
	v_exp_f32_e32 v179, v179
	v_min_f32_e32 v180, 0x42c80000, v180
	v_mul_f32_e32 v181, 0x3fb8aa3b, v181
	v_sub_f32_e32 v182, v187, v174
	v_exp_f32_e32 v180, v180
	v_min_f32_e32 v181, 0x42c80000, v181
	v_mul_f32_e32 v182, 0x3fb8aa3b, v182
	v_sub_f32_e32 v183, v186, v174
	v_exp_f32_e32 v181, v181
	v_min_f32_e32 v182, 0x42c80000, v182
	v_mul_f32_e32 v183, 0x3fb8aa3b, v183
	v_sub_f32_e32 v184, v185, v174
	v_add_f32_e32 v178, 0, v177
	v_exp_f32_e32 v182, v182
	v_min_f32_e32 v183, 0x42c80000, v183
	v_mul_f32_e32 v184, 0x3fb8aa3b, v184
	v_sub_f32_e32 v176, v176, v174
	v_add_f32_e32 v178, v179, v178
	v_exp_f32_e32 v183, v183
	v_min_f32_e32 v184, 0x42c80000, v184
	v_mul_f32_e32 v176, 0x3fb8aa3b, v176
	v_add_f32_e32 v178, v180, v178
	v_exp_f32_e32 v184, v184
	v_min_f32_e32 v176, 0x42c80000, v176
	v_add_f32_e32 v178, v181, v178
	v_exp_f32_e32 v185, v176
	v_add_f32_e32 v178, v182, v178
	v_add_f32_e32 v178, v183, v178
	v_add_f32_e32 v178, v184, v178
	v_add_f32_e32 v176, v185, v178
	v_add3_u32 v189, s67, v138, v131
	v_add_f32_e32 v140, v140, v176
	v_cvt_pk_bf16_f32 v176, v177, v179
	v_cvt_pk_bf16_f32 v177, v180, v181
	v_cvt_pk_bf16_f32 v178, v182, v183
	v_cvt_pk_bf16_f32 v179, v184, v185
	v_add3_u32 v188, s67, v137, v131
	ds_read_b64_tr_b16 v[216:217], v188 offset:17408
	ds_read_b64_tr_b16 v[218:219], v189 offset:17408
	ds_read_b64_tr_b16 v[220:221], v188 offset:17440
	ds_read_b64_tr_b16 v[222:223], v189 offset:17440
	ds_read_b64_tr_b16 v[224:225], v188 offset:17472
	ds_read_b64_tr_b16 v[226:227], v189 offset:17472
	ds_read_b64_tr_b16 v[228:229], v188 offset:17504
	ds_read_b64_tr_b16 v[230:231], v189 offset:17504
	ds_read_b64_tr_b16 v[232:233], v188 offset:17536
	ds_read_b64_tr_b16 v[234:235], v189 offset:17536
	ds_read_b64_tr_b16 v[236:237], v188 offset:17568
	ds_read_b64_tr_b16 v[238:239], v189 offset:17568
	ds_read_b64_tr_b16 v[180:181], v188 offset:17600
	ds_read_b64_tr_b16 v[182:183], v189 offset:17600
	s_waitcnt lgkmcnt(0)
	v_mfma_f32_16x16x32_bf16 v[76:79], v[216:219], v[176:179], v[76:79]
	ds_read_b64_tr_b16 v[216:217], v188 offset:17632
	ds_read_b64_tr_b16 v[218:219], v189 offset:17632
	v_mfma_f32_16x16x32_bf16 v[72:75], v[220:223], v[176:179], v[72:75]
	v_mfma_f32_16x16x32_bf16 v[64:67], v[224:227], v[176:179], v[64:67]
	v_mfma_f32_16x16x32_bf16 v[52:55], v[228:231], v[176:179], v[52:55]
	v_mfma_f32_16x16x32_bf16 v[48:51], v[232:235], v[176:179], v[48:51]
	v_mfma_f32_16x16x32_bf16 v[40:43], v[236:239], v[176:179], v[40:43]
	v_mfma_f32_16x16x32_bf16 v[28:31], v[180:183], v[176:179], v[28:31]
	s_waitcnt lgkmcnt(0)
	v_mfma_f32_16x16x32_bf16 v[24:27], v[216:219], v[176:179], v[24:27]
